# late transposes split: n_s=(bid>>3)&3 items before the first in-proj tile (work as stagger), rest after the last tile; write-through stores
# baseline (speedup 1.0000x reference)
.LBB0_260:
	s_cmp_lt_u32 s74, 32
	s_cbranch_scc1 .Lmy_ls_skip
	s_bfe_u32 s29, s74, 0x20003
	s_mul_i32 s28, s29, 0x700
	s_cmp_eq_u32 s29, 0
	s_cbranch_scc1 .Lmy_ls_skip
	s_add_i32 s28, s28, 0x98f
	s_movk_i32 s30, 0x990
	s_mov_b64 s[6:7], s[0:1]
	v_readlane_b32 s2, v253, 0
	v_readlane_b32 s3, v253, 1
	s_sub_u32 s2, s2, 0xf0
	s_subb_u32 s3, s3, 0
	s_load_dwordx4 s[88:91], s[2:3], 0xc0
	s_load_dwordx2 s[92:93], s[2:3], 0xd0
	s_movk_i32 s24, 0x700
	v_mov_b32_e32 v1, v202
	v_ashrrev_i32_e32 v2, 6, v1
	s_sub_i32 s0, s74, 32
	v_lshl_add_u32 v3, s0, 3, v2
	s_waitcnt lgkmcnt(0)
	s_movk_i32 s0, 0x700
	v_cmp_gt_i32_e32 vcc, s0, v3
	s_and_saveexec_b64 s[0:1], vcc
	s_cbranch_execz .Lmy_ls_170
	s_movk_i32 s2, 0x2100
	v_add_u32_e32 v5, s30, v3
	v_mul_lo_u32 v3, v2, s2
	v_and_b32_e32 v46, 31, v1
	v_bfe_u32 v2, v1, 5, 1
	v_bfe_u32 v47, v1, 3, 3
	v_lshlrev_b32_e32 v1, 3, v1
	v_and_b32_e32 v1, 56, v1
	v_readlane_b32 s8, v253, 2
	v_lshlrev_b32_e32 v6, 1, v1
	v_mov_b32_e32 v7, 0
	v_readlane_b32 s9, v253, 3
	s_mov_b64 s[2:3], 0x2080000
	v_add_u32_e32 v10, 0, v3
	v_lshl_add_u64 v[26:27], s[8:9], 0, v[6:7]
	v_lshlrev_b32_e32 v28, 2, v46
	v_mul_u32_u24_e32 v11, 0x84, v1
	v_lshl_add_u64 v[8:9], v[26:27], 0, s[2:3]
	v_lshlrev_b32_e32 v1, 2, v47
	s_mov_b64 s[2:3], 0x1c80000
	v_add_u32_e32 v4, v10, v28
	v_add3_u32 v48, v10, v11, v1
	v_lshl_add_u64 v[10:11], v[26:27], 0, s[2:3]
	s_mov_b64 s[2:3], 0x1480000
	v_lshl_add_u64 v[12:13], v[26:27], 0, s[2:3]
	s_mov_b64 s[2:3], 0x2480000
	v_lshl_add_u64 v[14:15], v[26:27], 0, s[2:3]
	s_mov_b64 s[2:3], 0x2780000
	v_lshl_add_u64 v[16:17], v[26:27], 0, s[2:3]
	s_mov_b64 s[2:3], 0x2680000
	v_lshl_add_u64 v[18:19], v[26:27], 0, s[2:3]
	s_mov_b64 s[2:3], 0x2950000
	v_lshl_add_u64 v[20:21], v[26:27], 0, s[2:3]
	s_mov_b64 s[2:3], 0x2910000
	v_lshl_add_u64 v[22:23], v[26:27], 0, s[2:3]
	s_mov_b64 s[2:3], 0x2880000
	v_lshl_add_u64 v[24:25], v[26:27], 0, s[2:3]
	s_mov_b64 s[2:3], 0xb00000
	v_mul_u32_u24_e32 v6, 0x84, v2
	v_lshl_add_u64 v[26:27], v[26:27], 0, s[2:3]
	s_add_u32 s2, s92, 0x800000
	v_or_b32_e32 v3, v3, v6
	s_movk_i32 s25, 0x84
	v_or_b32_e32 v49, 8, v47
	v_or_b32_e32 v50, 16, v47
	v_or_b32_e32 v51, 24, v47
	s_addc_u32 s3, s93, 0
	v_or_b32_e32 v52, 64, v46
	v_mov_b32_e32 v1, v2
	v_add3_u32 v53, v3, v28, 0
	v_or_b32_e32 v54, 14, v2
	v_or_b32_e32 v55, 12, v2
	v_or_b32_e32 v56, 10, v2
	v_or_b32_e32 v57, 8, v2
	v_or_b32_e32 v58, 6, v2
	v_or_b32_e32 v59, 4, v2
	v_or_b32_e32 v60, 2, v2
	s_mov_b64 s[4:5], 0
	s_movk_i32 s36, 0x97f
	s_movk_i32 s37, 0xc00
	s_movk_i32 s38, 0x4ac0
	v_mov_b32_e32 v61, 0x2c0
	v_mov_b32_e32 v62, 0x3c0
	v_mov_b32_e32 v63, 0xffffff80
	v_mov_b32_e32 v64, 5
	v_readlane_b32 s10, v253, 4
	v_readlane_b32 s11, v253, 5
	s_branch .Lmy_ls_79

.Lmy_ls_78:
	s_or_b64 exec, exec, s[8:9]
	v_add_u32_e32 v5, s24, v5
	s_mov_b32 s8, s28
	v_cmp_lt_i32_e32 vcc, s8, v5
	s_or_b64 s[4:5], vcc, s[4:5]
	s_andn2_b64 exec, exec, s[4:5]
	s_cbranch_execz .Lmy_ls_170

.Lmy_ls_170:
	s_or_b64 exec, exec, s[0:1]
	s_waitcnt vmcnt(0) lgkmcnt(0)
	s_mov_b64 s[0:1], s[6:7]

.LBB0_671:
	s_waitcnt vmcnt(0)
	s_barrier
	s_cmp_lt_u32 s74, 32
	s_cbranch_scc1 .Lmy_lt_skip
	s_bfe_u32 s29, s74, 0x20003
	s_mul_i32 s28, s29, 0x700
	s_cmp_eq_u32 s29, 3
	s_cbranch_scc1 .Lmy_lt_skip
	s_add_i32 s30, s28, 0x990
	s_movk_i32 s28, 0x1e8f
	v_readlane_b32 s2, v253, 0
	v_readlane_b32 s3, v253, 1
	s_sub_u32 s2, s2, 0xf0
	s_subb_u32 s3, s3, 0
	s_load_dwordx4 s[88:91], s[2:3], 0xc0
	s_load_dwordx2 s[92:93], s[2:3], 0xd0
	s_movk_i32 s24, 0x700
	v_mov_b32_e32 v1, v202
	v_ashrrev_i32_e32 v2, 6, v1
	s_sub_i32 s0, s74, 32
	v_lshl_add_u32 v3, s0, 3, v2
	s_waitcnt lgkmcnt(0)
	s_movk_i32 s0, 0x700
	v_cmp_gt_i32_e32 vcc, s0, v3
	s_and_saveexec_b64 s[0:1], vcc
	s_cbranch_execz .Lmy_lt_170
	s_movk_i32 s2, 0x2100
	v_add_u32_e32 v5, s30, v3
	v_mul_lo_u32 v3, v2, s2
	v_and_b32_e32 v46, 31, v1
	v_bfe_u32 v2, v1, 5, 1
	v_bfe_u32 v47, v1, 3, 3
	v_lshlrev_b32_e32 v1, 3, v1
	v_and_b32_e32 v1, 56, v1
	v_readlane_b32 s8, v253, 2
	v_lshlrev_b32_e32 v6, 1, v1
	v_mov_b32_e32 v7, 0
	v_readlane_b32 s9, v253, 3
	s_mov_b64 s[2:3], 0x2080000
	v_add_u32_e32 v10, 0, v3
	v_lshl_add_u64 v[26:27], s[8:9], 0, v[6:7]
	v_lshlrev_b32_e32 v28, 2, v46
	v_mul_u32_u24_e32 v11, 0x84, v1
	v_lshl_add_u64 v[8:9], v[26:27], 0, s[2:3]
	v_lshlrev_b32_e32 v1, 2, v47
	s_mov_b64 s[2:3], 0x1c80000
	v_add_u32_e32 v4, v10, v28
	v_add3_u32 v48, v10, v11, v1
	v_lshl_add_u64 v[10:11], v[26:27], 0, s[2:3]
	s_mov_b64 s[2:3], 0x1480000
	v_lshl_add_u64 v[12:13], v[26:27], 0, s[2:3]
	s_mov_b64 s[2:3], 0x2480000
	v_lshl_add_u64 v[14:15], v[26:27], 0, s[2:3]
	s_mov_b64 s[2:3], 0x2780000
	v_lshl_add_u64 v[16:17], v[26:27], 0, s[2:3]
	s_mov_b64 s[2:3], 0x2680000
	v_lshl_add_u64 v[18:19], v[26:27], 0, s[2:3]
	s_mov_b64 s[2:3], 0x2950000
	v_lshl_add_u64 v[20:21], v[26:27], 0, s[2:3]
	s_mov_b64 s[2:3], 0x2910000
	v_lshl_add_u64 v[22:23], v[26:27], 0, s[2:3]
	s_mov_b64 s[2:3], 0x2880000
	v_lshl_add_u64 v[24:25], v[26:27], 0, s[2:3]
	s_mov_b64 s[2:3], 0xb00000
	v_mul_u32_u24_e32 v6, 0x84, v2
	v_lshl_add_u64 v[26:27], v[26:27], 0, s[2:3]
	s_add_u32 s2, s92, 0x800000
	v_or_b32_e32 v3, v3, v6
	s_movk_i32 s25, 0x84
	v_or_b32_e32 v49, 8, v47
	v_or_b32_e32 v50, 16, v47
	v_or_b32_e32 v51, 24, v47
	s_addc_u32 s3, s93, 0
	v_or_b32_e32 v52, 64, v46
	v_mov_b32_e32 v1, v2
	v_add3_u32 v53, v3, v28, 0
	v_or_b32_e32 v54, 14, v2
	v_or_b32_e32 v55, 12, v2
	v_or_b32_e32 v56, 10, v2
	v_or_b32_e32 v57, 8, v2
	v_or_b32_e32 v58, 6, v2
	v_or_b32_e32 v59, 4, v2
	v_or_b32_e32 v60, 2, v2
	s_mov_b64 s[4:5], 0
	s_movk_i32 s36, 0x97f
	s_movk_i32 s37, 0xc00
	s_movk_i32 s38, 0x4ac0
	v_mov_b32_e32 v61, 0x2c0
	v_mov_b32_e32 v62, 0x3c0
	v_mov_b32_e32 v63, 0xffffff80
	v_mov_b32_e32 v64, 5
	v_readlane_b32 s10, v253, 4
	v_readlane_b32 s11, v253, 5
	s_branch .Lmy_lt_79
